# meta-row tails before the grid barriers: batched loads in the tiny GEMMs (phases 1, 2, 4, 6), in phase 4's residual add and in the meta-row rmsnorm gains (phases 0, 5)
# speedup vs baseline: 1.0279x; 1.0040x over previous
.LBB0_113:
	global_load_dwordx4 v[14:17], v[6:7], off offset:-3072
	global_load_dwordx4 v[18:21], v[6:7], off offset:-2048
	global_load_dwordx4 v[22:25], v[6:7], off
	global_load_dwordx4 v[26:29], v[6:7], off offset:-1024
	global_load_dwordx4 v[30:33], v[2:3], off
	global_load_dwordx4 v[80:83], v[2:3], off offset:1024
	global_load_dwordx4 v[84:87], v[2:3], off offset:2048
	global_load_dwordx4 v[88:91], v[2:3], off offset:3072
	v_add_u32_e32 v38, s6, v38
	v_lshl_add_u64 v[6:7], v[6:7], 0, s[4:5]
	s_waitcnt vmcnt(7)
	v_mov_b32_e32 v36, v15
	s_waitcnt vmcnt(6)
	v_mov_b32_e32 v37, v19
	v_mov_b32_e32 v34, v14
	v_mov_b32_e32 v35, v18
	s_waitcnt vmcnt(5)
	v_mov_b32_e32 v46, v23
	s_waitcnt vmcnt(4)
	v_mov_b32_e32 v47, v27
	v_pk_mul_f32 v[36:37], v[36:37], v[36:37]
	v_mov_b32_e32 v40, v16
	v_mov_b32_e32 v41, v20
	v_mov_b32_e32 v44, v22
	v_mov_b32_e32 v45, v26
	v_pk_mul_f32 v[46:47], v[46:47], v[46:47]
	v_pk_fma_f32 v[34:35], v[34:35], v[34:35], v[36:37]
	v_mov_b32_e32 v42, v17
	v_mov_b32_e32 v43, v21
	v_mov_b32_e32 v48, v24
	v_mov_b32_e32 v49, v28
	v_pk_fma_f32 v[36:37], v[44:45], v[44:45], v[46:47]
	v_pk_fma_f32 v[34:35], v[40:41], v[40:41], v[34:35]
	v_mov_b32_e32 v50, v25
	v_mov_b32_e32 v51, v29
	v_pk_fma_f32 v[36:37], v[48:49], v[48:49], v[36:37]
	v_pk_fma_f32 v[34:35], v[42:43], v[42:43], v[34:35]
	v_pk_fma_f32 v[36:37], v[50:51], v[50:51], v[36:37]
	v_add_f32_e32 v34, v34, v35
	v_add_f32_e32 v34, v37, v34
	v_add_f32_e32 v34, v36, v34
	ds_bpermute_b32 v35, v1, v34
	s_waitcnt lgkmcnt(0)
	v_add_f32_e32 v34, v34, v35
	ds_bpermute_b32 v35, v8, v34
	s_waitcnt lgkmcnt(0)
	v_add_f32_e32 v34, v34, v35
	ds_bpermute_b32 v35, v9, v34
	s_waitcnt lgkmcnt(0)
	v_add_f32_e32 v34, v34, v35
	ds_bpermute_b32 v35, v10, v34
	s_waitcnt lgkmcnt(0)
	v_add_f32_e32 v34, v34, v35
	ds_bpermute_b32 v35, v11, v34
	s_waitcnt lgkmcnt(0)
	v_add_f32_e32 v34, v34, v35
	ds_bpermute_b32 v35, v12, v34
	s_waitcnt lgkmcnt(0)
	v_add_f32_e32 v34, v34, v35
	v_fmamk_f32 v34, v34, 0x3a800000, v13
	v_mul_f32_e32 v35, 0x4b800000, v34
	v_cmp_gt_f32_e32 vcc, s7, v34
	s_nop 1
	v_cndmask_b32_e32 v34, v34, v35, vcc
	v_rsq_f32_e32 v34, v34
	s_nop 0
	v_mul_f32_e32 v35, 0x45800000, v34
	v_cndmask_b32_e32 v34, v34, v35, vcc
	v_pk_mul_f32 v[14:15], v[14:15], v[34:35] op_sel_hi:[1,0]
	v_pk_mul_f32 v[16:17], v[16:17], v[34:35] op_sel_hi:[1,0]
	s_waitcnt vmcnt(0)
	v_pk_mul_f32 v[14:15], v[30:31], v[14:15]
	v_pk_mul_f32 v[16:17], v[32:33], v[16:17]
	v_cvt_pk_bf16_f32 v14, v14, v15
	v_cvt_pk_bf16_f32 v15, v16, v17
	global_store_dwordx2 v[4:5], v[14:15], off
	v_pk_mul_f32 v[18:19], v[18:19], v[34:35] op_sel_hi:[1,0]
	v_pk_mul_f32 v[20:21], v[20:21], v[34:35] op_sel_hi:[1,0]
	v_cmp_lt_i32_e32 vcc, 15, v38
	s_or_b64 s[8:9], vcc, s[8:9]
	v_pk_mul_f32 v[16:17], v[82:83], v[20:21]
	v_pk_mul_f32 v[14:15], v[80:81], v[18:19]
	v_pk_mul_f32 v[18:19], v[26:27], v[34:35] op_sel_hi:[1,0]
	v_cvt_pk_bf16_f32 v14, v14, v15
	v_cvt_pk_bf16_f32 v15, v16, v17
	global_store_dwordx2 v[4:5], v[14:15], off offset:512
	v_pk_mul_f32 v[20:21], v[28:29], v[34:35] op_sel_hi:[1,0]
	v_pk_mul_f32 v[14:15], v[84:85], v[18:19]
	v_pk_mul_f32 v[16:17], v[86:87], v[20:21]
	v_cvt_pk_bf16_f32 v14, v14, v15
	v_cvt_pk_bf16_f32 v15, v16, v17
	global_store_dwordx2 v[4:5], v[14:15], off offset:1024
	v_pk_mul_f32 v[18:19], v[22:23], v[34:35] op_sel_hi:[1,0]
	v_pk_mul_f32 v[20:21], v[24:25], v[34:35] op_sel_hi:[1,0]
	v_pk_mul_f32 v[14:15], v[88:89], v[18:19]
	v_pk_mul_f32 v[16:17], v[90:91], v[20:21]
	v_cvt_pk_bf16_f32 v14, v14, v15
	v_cvt_pk_bf16_f32 v15, v16, v17
	global_store_dwordx2 v[4:5], v[14:15], off offset:1536
	v_lshl_add_u64 v[4:5], v[4:5], 0, s[2:3]
	s_andn2_b64 exec, exec, s[8:9]
	s_cbranch_execnz .LBB0_113

.LBB0_286:
	v_ashrrev_i32_e32 v33, 31, v32
	v_lshlrev_b64 v[6:7], 11, v[32:33]
	v_lshl_add_u64 v[40:41], v[14:15], 0, v[6:7]
	v_add_co_u32_e32 v66, vcc, 0x8000, v40
	s_nop 0
	v_addc_co_u32_e32 v67, vcc, 0, v41, vcc
	global_load_dwordx4 v[100:103], v[12:13], off
	global_load_dwordx4 v[104:107], v[40:41], off
	global_load_dwordx4 v[108:111], v[66:67], off
	global_load_dwordx4 v[112:115], v[12:13], off offset:64
	global_load_dwordx4 v[116:119], v[40:41], off offset:64
	global_load_dwordx4 v[120:123], v[66:67], off offset:64
	global_load_dwordx4 v[124:127], v[12:13], off offset:128
	global_load_dwordx4 v[128:131], v[40:41], off offset:128
	global_load_dwordx4 v[132:135], v[66:67], off offset:128
	global_load_dwordx4 v[136:139], v[12:13], off offset:192
	global_load_dwordx4 v[140:143], v[40:41], off offset:192
	global_load_dwordx4 v[144:147], v[66:67], off offset:192
	s_waitcnt vmcnt(0)
	v_mfma_f32_16x16x32_bf16 v[6:9], v[100:103], v[104:107], 0
	v_mfma_f32_16x16x32_bf16 v[2:5], v[100:103], v[108:111], 0
	v_mfma_f32_16x16x32_bf16 v[6:9], v[112:115], v[116:119], v[6:9]
	v_mfma_f32_16x16x32_bf16 v[2:5], v[112:115], v[120:123], v[2:5]
	v_mfma_f32_16x16x32_bf16 v[6:9], v[124:127], v[128:131], v[6:9]
	v_mfma_f32_16x16x32_bf16 v[2:5], v[124:127], v[132:135], v[2:5]
	v_mfma_f32_16x16x32_bf16 v[6:9], v[136:139], v[140:143], v[6:9]
	v_mfma_f32_16x16x32_bf16 v[2:5], v[136:139], v[144:147], v[2:5]
	s_nop 5
	ds_write_b128 v1, v[6:9]
	s_nop 0
	ds_write_b128 v1, v[2:5] offset:1024
	s_waitcnt lgkmcnt(0)
	s_barrier
	s_and_saveexec_b64 s[8:9], s[2:3]
	s_cbranch_execz .LBB0_288
	ds_read_b128 v[36:39], v42 offset:2048
	ds_read_b128 v[46:49], v42 offset:3072
	ds_read_b128 v[50:53], v42 offset:4096
	s_waitcnt lgkmcnt(2)
	v_pk_add_f32 v[40:41], v[6:7], v[36:37]
	s_waitcnt lgkmcnt(1)
	v_pk_add_f32 v[48:49], v[4:5], v[48:49]
	ds_read_b128 v[4:7], v42 offset:5120
	v_pk_add_f32 v[8:9], v[8:9], v[38:39]
	v_pk_add_f32 v[2:3], v[2:3], v[46:47]
	ds_read_b128 v[36:39], v42 offset:6144
	s_waitcnt lgkmcnt(2)
	v_pk_add_f32 v[46:47], v[8:9], v[52:53]
	v_pk_add_f32 v[40:41], v[40:41], v[50:51]
	s_waitcnt lgkmcnt(1)
	v_pk_add_f32 v[48:49], v[48:49], v[6:7]
	ds_read_b128 v[6:9], v42 offset:7168
	v_pk_add_f32 v[50:51], v[2:3], v[4:5]
	ds_read_b128 v[2:5], v42 offset:8192
	s_waitcnt lgkmcnt(2)
	v_pk_add_f32 v[46:47], v[46:47], v[38:39]
	v_pk_add_f32 v[40:41], v[40:41], v[36:37]
	s_waitcnt lgkmcnt(1)
	v_pk_add_f32 v[8:9], v[48:49], v[8:9]
	ds_read_b128 v[36:39], v42 offset:9216
	v_pk_add_f32 v[48:49], v[50:51], v[6:7]
	s_waitcnt lgkmcnt(1)
	v_pk_add_f32 v[46:47], v[46:47], v[4:5]
	ds_read_b128 v[4:7], v42 offset:10240
	v_pk_add_f32 v[2:3], v[40:41], v[2:3]
	s_waitcnt lgkmcnt(1)
	v_pk_add_f32 v[50:51], v[8:9], v[38:39]
	ds_read_b128 v[38:41], v42 offset:11264
	v_pk_add_f32 v[36:37], v[48:49], v[36:37]
	s_waitcnt lgkmcnt(1)
	v_pk_add_f32 v[46:47], v[46:47], v[6:7]
	ds_read_b128 v[6:9], v42 offset:12288
	v_pk_add_f32 v[48:49], v[2:3], v[4:5]
	ds_read_b128 v[2:5], v42 offset:13312
	s_waitcnt lgkmcnt(2)
	v_pk_add_f32 v[40:41], v[50:51], v[40:41]
	v_pk_add_f32 v[50:51], v[36:37], v[38:39]
	s_waitcnt lgkmcnt(1)
	v_pk_add_f32 v[8:9], v[46:47], v[8:9]
	ds_read_b128 v[36:39], v42 offset:14336
	v_pk_add_f32 v[6:7], v[48:49], v[6:7]
	ds_read_b128 v[46:49], v42 offset:15360
	s_waitcnt lgkmcnt(2)
	v_pk_add_f32 v[4:5], v[40:41], v[4:5]
	v_pk_add_f32 v[2:3], v[50:51], v[2:3]
	s_waitcnt lgkmcnt(1)
	v_pk_add_f32 v[8:9], v[8:9], v[38:39]
	v_pk_add_f32 v[6:7], v[6:7], v[36:37]
	s_waitcnt lgkmcnt(0)
	v_pk_add_f32 v[4:5], v[4:5], v[48:49]
	v_pk_add_f32 v[2:3], v[2:3], v[46:47]

.LBB0_442:
	s_cmp_gt_u32 s25, 39
	s_cselect_b64 s[4:5], -1, 0
	s_and_b64 s[8:9], s[4:5], exec
	s_cselect_b32 s0, s12, 0xffffffe8
	s_add_i32 s0, s0, s25
	s_and_b64 s[8:9], s[4:5], exec
	s_cselect_b32 s8, s13, 0x660000
	v_lshl_or_b32 v40, s0, 5, v1
	s_add_u32 s8, s20, s8
	v_ashrrev_i32_e32 v41, 31, v40
	s_addc_u32 s9, s21, 0
	v_lshlrev_b64 v[2:3], 9, v[40:41]
	v_lshl_add_u64 v[6:7], s[8:9], 0, v[2:3]
	global_load_dwordx4 v[2:5], v[12:13], off
	v_lshl_add_u64 v[6:7], v[6:7], 0, v[10:11]
	v_mov_b32_e32 v39, v11
	v_lshl_add_u64 v[42:43], v[6:7], 0, v[38:39]
	global_load_dwordx4 v[6:9], v[42:43], off
	v_add_co_u32_e32 v42, vcc, s14, v42
	s_nop 0
	v_addc_co_u32_e32 v43, vcc, 0, v43, vcc
	global_load_dwordx4 v[58:61], v[42:43], off
	s_waitcnt vmcnt(0)
	v_mfma_f32_16x16x32_bf16 v[6:9], v[2:5], v[6:9], 0
	v_mfma_f32_16x16x32_bf16 v[2:5], v[2:5], v[58:61], 0
	s_nop 7
	ds_write_b128 v56, v[6:9]
	s_nop 2
	ds_write_b128 v56, v[2:5] offset:1024
	s_waitcnt lgkmcnt(0)
	s_barrier
	s_and_saveexec_b64 s[8:9], s[2:3]
	s_cbranch_execz .LBB0_444
	ds_read_b128 v[58:61], v44 offset:2048
	ds_read_b128 v[62:65], v44 offset:3072
	ds_read_b128 v[66:69], v44 offset:4096
	s_waitcnt lgkmcnt(2)
	v_pk_add_f32 v[42:43], v[6:7], v[58:59]
	s_waitcnt lgkmcnt(1)
	v_pk_add_f32 v[64:65], v[4:5], v[64:65]
	ds_read_b128 v[4:7], v44 offset:5120
	v_pk_add_f32 v[8:9], v[8:9], v[60:61]
	v_pk_add_f32 v[2:3], v[2:3], v[62:63]
	ds_read_b128 v[58:61], v44 offset:6144
	s_waitcnt lgkmcnt(2)
	v_pk_add_f32 v[62:63], v[8:9], v[68:69]
	v_pk_add_f32 v[42:43], v[42:43], v[66:67]
	s_waitcnt lgkmcnt(1)
	v_pk_add_f32 v[64:65], v[64:65], v[6:7]
	ds_read_b128 v[6:9], v44 offset:7168
	v_pk_add_f32 v[66:67], v[2:3], v[4:5]
	ds_read_b128 v[2:5], v44 offset:8192
	s_waitcnt lgkmcnt(2)
	v_pk_add_f32 v[62:63], v[62:63], v[60:61]
	v_pk_add_f32 v[42:43], v[42:43], v[58:59]
	s_waitcnt lgkmcnt(1)
	v_pk_add_f32 v[8:9], v[64:65], v[8:9]
	ds_read_b128 v[58:61], v44 offset:9216
	v_pk_add_f32 v[64:65], v[66:67], v[6:7]
	s_waitcnt lgkmcnt(1)
	v_pk_add_f32 v[66:67], v[62:63], v[4:5]
	ds_read_b128 v[4:7], v44 offset:10240
	v_pk_add_f32 v[2:3], v[42:43], v[2:3]
	s_waitcnt lgkmcnt(1)
	v_pk_add_f32 v[42:43], v[8:9], v[60:61]
	ds_read_b128 v[60:63], v44 offset:11264
	v_pk_add_f32 v[58:59], v[64:65], v[58:59]
	s_waitcnt lgkmcnt(1)
	v_pk_add_f32 v[64:65], v[66:67], v[6:7]
	ds_read_b128 v[6:9], v44 offset:12288
	v_pk_add_f32 v[66:67], v[2:3], v[4:5]
	ds_read_b128 v[2:5], v44 offset:13312
	s_waitcnt lgkmcnt(2)
	v_pk_add_f32 v[42:43], v[42:43], v[62:63]
	v_pk_add_f32 v[68:69], v[58:59], v[60:61]
	s_waitcnt lgkmcnt(1)
	v_pk_add_f32 v[8:9], v[64:65], v[8:9]
	ds_read_b128 v[58:61], v44 offset:14336
	ds_read_b128 v[62:65], v44 offset:15360
	v_pk_add_f32 v[6:7], v[66:67], v[6:7]
	s_waitcnt lgkmcnt(2)
	v_pk_add_f32 v[4:5], v[42:43], v[4:5]
	v_pk_add_f32 v[2:3], v[68:69], v[2:3]
	s_waitcnt lgkmcnt(1)
	v_pk_add_f32 v[8:9], v[8:9], v[60:61]
	v_pk_add_f32 v[6:7], v[6:7], v[58:59]
	s_waitcnt lgkmcnt(0)
	v_pk_add_f32 v[4:5], v[4:5], v[64:65]
	v_pk_add_f32 v[2:3], v[2:3], v[62:63]

.LBB0_447:
	v_lshl_or_b32 v40, s25, 5, v1
	v_ashrrev_i32_e32 v41, 31, v40
	global_load_dwordx4 v[6:9], v[16:17], off
	v_lshlrev_b64 v[2:3], 9, v[40:41]
	v_lshl_add_u64 v[42:43], v[18:19], 0, v[2:3]
	global_load_dwordx4 v[2:5], v[42:43], off
	v_add_co_u32_e32 v42, vcc, 0x2000, v42
	s_nop 0
	v_addc_co_u32_e32 v43, vcc, 0, v43, vcc
	global_load_dwordx4 v[58:61], v[42:43], off
	s_waitcnt vmcnt(0)
	v_mfma_f32_16x16x32_bf16 v[2:5], v[6:9], v[2:5], 0
	v_mfma_f32_16x16x32_bf16 v[6:9], v[6:9], v[58:61], 0
	s_nop 7
	ds_write_b128 v56, v[2:5]
	s_nop 2
	ds_write_b128 v56, v[6:9] offset:1024
	s_waitcnt lgkmcnt(0)
	s_barrier
	s_and_saveexec_b64 s[4:5], s[2:3]
	s_cbranch_execz .LBB0_449
	ds_read_b128 v[58:61], v44 offset:2048
	ds_read_b128 v[62:65], v44 offset:3072
	ds_read_b128 v[66:69], v44 offset:4096
	s_waitcnt lgkmcnt(2)
	v_pk_add_f32 v[42:43], v[4:5], v[60:61]
	v_pk_add_f32 v[58:59], v[2:3], v[58:59]
	ds_read_b128 v[2:5], v44 offset:5120
	s_waitcnt lgkmcnt(2)
	v_pk_add_f32 v[60:61], v[8:9], v[64:65]
	v_pk_add_f32 v[62:63], v[6:7], v[62:63]
	ds_read_b128 v[6:9], v44 offset:6144
	s_waitcnt lgkmcnt(2)
	v_pk_add_f32 v[42:43], v[42:43], v[68:69]
	v_pk_add_f32 v[64:65], v[58:59], v[66:67]
	s_waitcnt lgkmcnt(1)
	v_pk_add_f32 v[66:67], v[60:61], v[4:5]
	ds_read_b128 v[58:61], v44 offset:7168
	v_pk_add_f32 v[62:63], v[62:63], v[2:3]
	ds_read_b128 v[2:5], v44 offset:8192
	s_waitcnt lgkmcnt(2)
	v_pk_add_f32 v[42:43], v[42:43], v[8:9]
	v_pk_add_f32 v[64:65], v[64:65], v[6:7]
	ds_read_b128 v[6:9], v44 offset:9216
	s_waitcnt lgkmcnt(2)
	v_pk_add_f32 v[66:67], v[66:67], v[60:61]
	v_pk_add_f32 v[62:63], v[62:63], v[58:59]
	s_waitcnt lgkmcnt(1)
	v_pk_add_f32 v[42:43], v[42:43], v[4:5]
	ds_read_b128 v[58:61], v44 offset:10240
	v_pk_add_f32 v[64:65], v[64:65], v[2:3]
	ds_read_b128 v[2:5], v44 offset:11264
	s_waitcnt lgkmcnt(2)
	v_pk_add_f32 v[66:67], v[66:67], v[8:9]
	v_pk_add_f32 v[62:63], v[62:63], v[6:7]
	ds_read_b128 v[6:9], v44 offset:12288
	s_waitcnt lgkmcnt(2)
	v_pk_add_f32 v[42:43], v[42:43], v[60:61]
	v_pk_add_f32 v[64:65], v[64:65], v[58:59]
	s_waitcnt lgkmcnt(1)
	v_pk_add_f32 v[66:67], v[66:67], v[4:5]
	v_pk_add_f32 v[62:63], v[62:63], v[2:3]
	ds_read_b128 v[2:5], v44 offset:13312
	ds_read_b128 v[58:61], v44 offset:14336
	s_waitcnt lgkmcnt(2)
	v_pk_add_f32 v[42:43], v[42:43], v[8:9]
	v_pk_add_f32 v[64:65], v[64:65], v[6:7]
	ds_read_b128 v[6:9], v44 offset:15360
	s_waitcnt lgkmcnt(2)
	v_pk_add_f32 v[66:67], v[66:67], v[4:5]
	v_pk_add_f32 v[62:63], v[62:63], v[2:3]
	s_waitcnt lgkmcnt(1)
	v_pk_add_f32 v[4:5], v[42:43], v[60:61]
	v_pk_add_f32 v[2:3], v[64:65], v[58:59]
	s_waitcnt lgkmcnt(0)
	v_pk_add_f32 v[8:9], v[66:67], v[8:9]
	v_pk_add_f32 v[6:7], v[62:63], v[6:7]

.LBB0_968:
	v_ashrrev_i32_e32 v15, 31, v14
	v_lshlrev_b64 v[6:7], 11, v[14:15]
	v_lshl_add_u64 v[44:45], v[12:13], 0, v[6:7]
	v_add_co_u32_e32 v46, vcc, 0x8000, v44
	s_nop 0
	v_addc_co_u32_e32 v47, vcc, 0, v45, vcc
	global_load_dwordx4 v[48:51], v[10:11], off
	global_load_dwordx4 v[64:67], v[44:45], off
	global_load_dwordx4 v[80:83], v[46:47], off
	global_load_dwordx4 v[52:55], v[10:11], off offset:64
	global_load_dwordx4 v[68:71], v[44:45], off offset:64
	global_load_dwordx4 v[84:87], v[46:47], off offset:64
	global_load_dwordx4 v[56:59], v[10:11], off offset:128
	global_load_dwordx4 v[72:75], v[44:45], off offset:128
	global_load_dwordx4 v[88:91], v[46:47], off offset:128
	global_load_dwordx4 v[60:63], v[10:11], off offset:192
	global_load_dwordx4 v[76:79], v[44:45], off offset:192
	global_load_dwordx4 v[92:95], v[46:47], off offset:192
	s_and_saveexec_b64 s[4:5], s[2:3]
	v_add_u32_e32 v104, v18, v14
	v_lshlrev_b32_e32 v104, 2, v104
	v_add_u32_e32 v105, 0x1000, v104
	v_add_u32_e32 v106, 0x2000, v104
	v_add_u32_e32 v107, 0x3000, v104
	global_load_dword v96, v104, s[38:39]
	global_load_dword v97, v104, s[38:39] offset:64
	global_load_dword v98, v105, s[38:39]
	global_load_dword v99, v105, s[38:39] offset:64
	global_load_dword v100, v106, s[38:39]
	global_load_dword v101, v106, s[38:39] offset:64
	global_load_dword v102, v107, s[38:39]
	global_load_dword v103, v107, s[38:39] offset:64
	s_or_b64 exec, exec, s[4:5]
	s_waitcnt vmcnt(0)
	v_mfma_f32_16x16x32_bf16 v[6:9], v[48:51], v[64:67], 0
	v_mfma_f32_16x16x32_bf16 v[2:5], v[48:51], v[80:83], 0
	v_mfma_f32_16x16x32_bf16 v[6:9], v[52:55], v[68:71], v[6:9]
	v_mfma_f32_16x16x32_bf16 v[2:5], v[52:55], v[84:87], v[2:5]
	v_mfma_f32_16x16x32_bf16 v[6:9], v[56:59], v[72:75], v[6:9]
	v_mfma_f32_16x16x32_bf16 v[2:5], v[56:59], v[88:91], v[2:5]
	v_mfma_f32_16x16x32_bf16 v[6:9], v[60:63], v[76:79], v[6:9]
	v_mfma_f32_16x16x32_bf16 v[2:5], v[60:63], v[92:95], v[2:5]
	s_nop 5
	ds_write_b128 v1, v[6:9]
	s_nop 0
	ds_write_b128 v1, v[2:5] offset:1024
	s_waitcnt lgkmcnt(0)
	s_barrier
	s_and_saveexec_b64 s[4:5], s[2:3]
	s_cbranch_execz .LBB0_970
	ds_read_b128 v[20:23], v16 offset:2048
	ds_read_b128 v[24:27], v16 offset:3072
	ds_read_b128 v[28:31], v16 offset:4096
	s_waitcnt lgkmcnt(2)
	v_pk_add_f32 v[32:33], v[6:7], v[20:21]
	s_waitcnt lgkmcnt(1)
	v_pk_add_f32 v[26:27], v[4:5], v[26:27]
	ds_read_b128 v[4:7], v16 offset:5120
	v_pk_add_f32 v[8:9], v[8:9], v[22:23]
	v_pk_add_f32 v[2:3], v[2:3], v[24:25]
	ds_read_b128 v[20:23], v16 offset:6144
	s_waitcnt lgkmcnt(2)
	v_pk_add_f32 v[24:25], v[8:9], v[30:31]
	s_waitcnt lgkmcnt(1)
	v_pk_add_f32 v[26:27], v[26:27], v[6:7]
	ds_read_b128 v[6:9], v16 offset:7168
	v_pk_add_f32 v[30:31], v[2:3], v[4:5]
	ds_read_b128 v[2:5], v16 offset:8192
	v_pk_add_f32 v[28:29], v[32:33], v[28:29]
	s_waitcnt lgkmcnt(2)
	v_pk_add_f32 v[24:25], v[24:25], v[22:23]
	v_pk_add_f32 v[28:29], v[28:29], v[20:21]
	s_waitcnt lgkmcnt(1)
	v_pk_add_f32 v[8:9], v[26:27], v[8:9]
	ds_read_b128 v[20:23], v16 offset:9216
	v_pk_add_f32 v[26:27], v[30:31], v[6:7]
	s_waitcnt lgkmcnt(1)
	v_pk_add_f32 v[30:31], v[24:25], v[4:5]
	ds_read_b128 v[4:7], v16 offset:10240
	v_pk_add_f32 v[2:3], v[28:29], v[2:3]
	s_waitcnt lgkmcnt(1)
	v_pk_add_f32 v[28:29], v[8:9], v[22:23]
	ds_read_b128 v[22:25], v16 offset:11264
	v_pk_add_f32 v[20:21], v[26:27], v[20:21]
	s_waitcnt lgkmcnt(1)
	v_pk_add_f32 v[26:27], v[30:31], v[6:7]
	ds_read_b128 v[6:9], v16 offset:12288
	v_pk_add_f32 v[30:31], v[2:3], v[4:5]
	ds_read_b128 v[2:5], v16 offset:13312
	s_waitcnt lgkmcnt(2)
	v_pk_add_f32 v[28:29], v[28:29], v[24:25]
	v_pk_add_f32 v[32:33], v[20:21], v[22:23]
	s_waitcnt lgkmcnt(1)
	v_pk_add_f32 v[8:9], v[26:27], v[8:9]
	ds_read_b128 v[20:23], v16 offset:14336
	ds_read_b128 v[24:27], v16 offset:15360
	v_pk_add_f32 v[6:7], v[30:31], v[6:7]
	s_waitcnt lgkmcnt(2)
	v_pk_add_f32 v[4:5], v[28:29], v[4:5]
	v_pk_add_f32 v[2:3], v[32:33], v[2:3]
	s_waitcnt lgkmcnt(1)
	v_pk_add_f32 v[8:9], v[8:9], v[22:23]
	v_pk_add_f32 v[6:7], v[6:7], v[20:21]
	s_waitcnt lgkmcnt(0)
	v_pk_add_f32 v[4:5], v[4:5], v[26:27]
	v_pk_add_f32 v[2:3], v[2:3], v[24:25]
.LBB0_970:
	s_or_b64 exec, exec, s[4:5]
	s_barrier
	s_and_saveexec_b64 s[4:5], s[2:3]
	s_cbranch_execz .LBB0_967
	v_add_f32_e32 v96, v6, v96
	v_add_f32_e32 v97, v2, v97
	v_add_f32_e32 v98, v7, v98
	v_add_f32_e32 v99, v3, v99
	v_add_f32_e32 v100, v8, v100
	v_add_f32_e32 v101, v4, v101
	v_add_f32_e32 v102, v9, v102
	v_add_f32_e32 v103, v5, v103
	global_store_dword v104, v96, s[0:1]
	global_store_dword v104, v97, s[0:1] offset:64
	global_store_dword v105, v98, s[0:1]
	global_store_dword v105, v99, s[0:1] offset:64
	global_store_dword v106, v100, s[0:1]
	global_store_dword v106, v101, s[0:1] offset:64
	global_store_dword v107, v102, s[0:1]
	global_store_dword v107, v103, s[0:1] offset:64
	s_branch .LBB0_967

.LBB0_1056:
	v_lshl_add_u64 v[20:21], s[20:21], 0, v[10:11]
	v_add_co_u32_e32 v32, vcc, 0x1a01a000, v20
	v_add_u32_e32 v18, s4, v18
	s_nop 0
	v_addc_co_u32_e32 v33, vcc, 0, v21, vcc
	v_add_co_u32_e32 v20, vcc, 0x1a01b000, v20
	global_load_dwordx4 v[24:27], v[32:33], off offset:2048
	global_load_dwordx4 v[28:31], v[32:33], off offset:3072
	v_addc_co_u32_e32 v21, vcc, 0, v21, vcc
	global_load_dwordx4 v[32:35], v[20:21], off offset:1024
	global_load_dwordx4 v[36:39], v[20:21], off
	global_load_dwordx4 v[40:43], v[2:3], off
	global_load_dwordx4 v[180:183], v[4:5], off
	global_load_dwordx4 v[184:187], v[6:7], off
	global_load_dwordx4 v[188:191], v[8:9], off
	v_lshl_add_u64 v[20:21], s[20:21], 0, v[12:13]
	v_add_co_u32_e32 v20, vcc, s10, v20
	v_lshl_add_u64 v[10:11], v[10:11], 0, s[2:3]
	s_nop 0
	v_addc_co_u32_e32 v21, vcc, 0, v21, vcc
	v_lshl_add_u64 v[12:13], v[12:13], 0, s[6:7]
	s_waitcnt vmcnt(0)
	v_mov_b32_e32 v46, v25
	v_mov_b32_e32 v47, v29
	v_mov_b32_e32 v44, v24
	v_mov_b32_e32 v45, v28
	v_pk_mul_f32 v[46:47], v[46:47], v[46:47]
	v_mov_b32_e32 v54, v33
	v_mov_b32_e32 v55, v37
	v_mov_b32_e32 v48, v26
	v_mov_b32_e32 v49, v30
	v_mov_b32_e32 v52, v32
	v_mov_b32_e32 v53, v36
	v_pk_fma_f32 v[44:45], v[44:45], v[44:45], v[46:47]
	v_pk_mul_f32 v[46:47], v[54:55], v[54:55]
	v_mov_b32_e32 v50, v27
	v_mov_b32_e32 v51, v31
	v_mov_b32_e32 v56, v34
	v_mov_b32_e32 v57, v38
	v_pk_fma_f32 v[44:45], v[48:49], v[48:49], v[44:45]
	v_pk_fma_f32 v[46:47], v[52:53], v[52:53], v[46:47]
	v_mov_b32_e32 v58, v35
	v_mov_b32_e32 v59, v39
	v_pk_fma_f32 v[44:45], v[50:51], v[50:51], v[44:45]
	v_pk_fma_f32 v[46:47], v[56:57], v[56:57], v[46:47]
	v_add_f32_e32 v19, v44, v45
	v_pk_fma_f32 v[46:47], v[58:59], v[58:59], v[46:47]
	s_nop 0
	v_add_f32_e32 v19, v47, v19
	v_add_f32_e32 v19, v46, v19
	ds_bpermute_b32 v44, v14, v19
	s_waitcnt lgkmcnt(0)
	v_add_f32_e32 v19, v19, v44
	ds_bpermute_b32 v44, v15, v19
	s_waitcnt lgkmcnt(0)
	v_add_f32_e32 v19, v19, v44
	ds_bpermute_b32 v44, v16, v19
	s_waitcnt lgkmcnt(0)
	v_add_f32_e32 v19, v19, v44
	ds_bpermute_b32 v44, v17, v19
	s_waitcnt lgkmcnt(0)
	v_add_f32_e32 v19, v19, v44
	ds_bpermute_b32 v44, v22, v19
	s_waitcnt lgkmcnt(0)
	v_add_f32_e32 v19, v19, v44
	ds_bpermute_b32 v44, v23, v19
	s_waitcnt lgkmcnt(0)
	v_add_f32_e32 v19, v19, v44
	v_fmamk_f32 v19, v19, 0x3a800000, v1
	v_mul_f32_e32 v44, 0x4b800000, v19
	v_cmp_gt_f32_e32 vcc, s5, v19
	s_nop 1
	v_cndmask_b32_e32 v19, v19, v44, vcc
	v_rsq_f32_e32 v19, v19
	s_nop 0
	v_mul_f32_e32 v44, 0x45800000, v19
	v_cndmask_b32_e32 v44, v19, v44, vcc
	v_pk_mul_f32 v[24:25], v[24:25], v[44:45] op_sel_hi:[1,0]
	v_pk_mul_f32 v[26:27], v[26:27], v[44:45] op_sel_hi:[1,0]
	v_pk_mul_f32 v[24:25], v[40:41], v[24:25]
	v_pk_mul_f32 v[26:27], v[42:43], v[26:27]
	v_cvt_pk_bf16_f32 v24, v24, v25
	v_cvt_pk_bf16_f32 v25, v26, v27
	global_store_dwordx2 v[20:21], v[24:25], off offset:2048
	v_pk_mul_f32 v[28:29], v[28:29], v[44:45] op_sel_hi:[1,0]
	v_pk_mul_f32 v[30:31], v[30:31], v[44:45] op_sel_hi:[1,0]
	v_cmp_lt_i32_e32 vcc, 15, v18
	s_or_b64 s[8:9], vcc, s[8:9]
	v_pk_mul_f32 v[26:27], v[182:183], v[30:31]
	v_pk_mul_f32 v[24:25], v[180:181], v[28:29]
	v_pk_mul_f32 v[28:29], v[36:37], v[44:45] op_sel_hi:[1,0]
	v_cvt_pk_bf16_f32 v24, v24, v25
	v_cvt_pk_bf16_f32 v25, v26, v27
	global_store_dwordx2 v[20:21], v[24:25], off offset:2560
	v_pk_mul_f32 v[30:31], v[38:39], v[44:45] op_sel_hi:[1,0]
	v_pk_mul_f32 v[24:25], v[184:185], v[28:29]
	v_pk_mul_f32 v[26:27], v[186:187], v[30:31]
	v_cvt_pk_bf16_f32 v24, v24, v25
	v_cvt_pk_bf16_f32 v25, v26, v27
	global_store_dwordx2 v[20:21], v[24:25], off offset:3072
	v_pk_mul_f32 v[28:29], v[32:33], v[44:45] op_sel_hi:[1,0]
	v_pk_mul_f32 v[30:31], v[34:35], v[44:45] op_sel_hi:[1,0]
	v_pk_mul_f32 v[24:25], v[188:189], v[28:29]
	v_pk_mul_f32 v[26:27], v[190:191], v[30:31]
	v_cvt_pk_bf16_f32 v24, v24, v25
	v_cvt_pk_bf16_f32 v25, v26, v27
	global_store_dwordx2 v[20:21], v[24:25], off offset:3584
	s_andn2_b64 exec, exec, s[8:9]
	s_cbranch_execnz .LBB0_1056

.LBB0_1149:
	v_add_u32_e32 v2, s8, v1
	v_ashrrev_i32_e32 v3, 31, v2
	v_lshlrev_b64 v[6:7], 11, v[2:3]
	v_lshl_add_u64 v[46:47], v[12:13], 0, v[6:7]
	v_add_co_u32_e32 v48, vcc, 0x8000, v46
	s_nop 0
	v_addc_co_u32_e32 v49, vcc, 0, v47, vcc
	global_load_dwordx4 v[100:103], v[10:11], off
	global_load_dwordx4 v[104:107], v[46:47], off
	global_load_dwordx4 v[108:111], v[48:49], off
	global_load_dwordx4 v[112:115], v[10:11], off offset:64
	global_load_dwordx4 v[116:119], v[46:47], off offset:64
	global_load_dwordx4 v[120:123], v[48:49], off offset:64
	global_load_dwordx4 v[124:127], v[10:11], off offset:128
	global_load_dwordx4 v[128:131], v[46:47], off offset:128
	global_load_dwordx4 v[132:135], v[48:49], off offset:128
	global_load_dwordx4 v[136:139], v[10:11], off offset:192
	global_load_dwordx4 v[140:143], v[46:47], off offset:192
	global_load_dwordx4 v[144:147], v[48:49], off offset:192
	s_waitcnt vmcnt(0)
	v_mfma_f32_16x16x32_bf16 v[6:9], v[100:103], v[104:107], 0
	v_mfma_f32_16x16x32_bf16 v[2:5], v[100:103], v[108:111], 0
	v_mfma_f32_16x16x32_bf16 v[6:9], v[112:115], v[116:119], v[6:9]
	v_mfma_f32_16x16x32_bf16 v[2:5], v[112:115], v[120:123], v[2:5]
	v_mfma_f32_16x16x32_bf16 v[6:9], v[124:127], v[128:131], v[6:9]
	v_mfma_f32_16x16x32_bf16 v[2:5], v[124:127], v[132:135], v[2:5]
	v_mfma_f32_16x16x32_bf16 v[6:9], v[136:139], v[140:143], v[6:9]
	v_mfma_f32_16x16x32_bf16 v[2:5], v[136:139], v[144:147], v[2:5]
	s_nop 5
	ds_write_b128 v20, v[6:9]
	s_nop 0
	ds_write_b128 v20, v[2:5] offset:1024
	s_waitcnt lgkmcnt(0)
	s_barrier
	s_and_saveexec_b64 s[6:7], s[2:3]
	s_cbranch_execz .LBB0_1151
	ds_read_b128 v[22:25], v14 offset:2048
	ds_read_b128 v[26:29], v14 offset:3072
	ds_read_b128 v[30:33], v14 offset:4096
	s_waitcnt lgkmcnt(2)
	v_pk_add_f32 v[34:35], v[6:7], v[22:23]
	s_waitcnt lgkmcnt(1)
	v_pk_add_f32 v[28:29], v[4:5], v[28:29]
	ds_read_b128 v[4:7], v14 offset:5120
	v_pk_add_f32 v[8:9], v[8:9], v[24:25]
	v_pk_add_f32 v[2:3], v[2:3], v[26:27]
	ds_read_b128 v[22:25], v14 offset:6144
	s_waitcnt lgkmcnt(2)
	v_pk_add_f32 v[26:27], v[8:9], v[32:33]
	s_waitcnt lgkmcnt(1)
	v_pk_add_f32 v[28:29], v[28:29], v[6:7]
	ds_read_b128 v[6:9], v14 offset:7168
	v_pk_add_f32 v[32:33], v[2:3], v[4:5]
	ds_read_b128 v[2:5], v14 offset:8192
	v_pk_add_f32 v[30:31], v[34:35], v[30:31]
	s_waitcnt lgkmcnt(2)
	v_pk_add_f32 v[26:27], v[26:27], v[24:25]
	v_pk_add_f32 v[30:31], v[30:31], v[22:23]
	s_waitcnt lgkmcnt(1)
	v_pk_add_f32 v[8:9], v[28:29], v[8:9]
	ds_read_b128 v[22:25], v14 offset:9216
	v_pk_add_f32 v[28:29], v[32:33], v[6:7]
	s_waitcnt lgkmcnt(1)
	v_pk_add_f32 v[32:33], v[26:27], v[4:5]
	ds_read_b128 v[4:7], v14 offset:10240
	v_pk_add_f32 v[2:3], v[30:31], v[2:3]
	s_waitcnt lgkmcnt(1)
	v_pk_add_f32 v[30:31], v[8:9], v[24:25]
	ds_read_b128 v[24:27], v14 offset:11264
	v_pk_add_f32 v[22:23], v[28:29], v[22:23]
	s_waitcnt lgkmcnt(1)
	v_pk_add_f32 v[28:29], v[32:33], v[6:7]
	ds_read_b128 v[6:9], v14 offset:12288
	v_pk_add_f32 v[32:33], v[2:3], v[4:5]
	ds_read_b128 v[2:5], v14 offset:13312
	s_waitcnt lgkmcnt(2)
	v_pk_add_f32 v[30:31], v[30:31], v[26:27]
	v_pk_add_f32 v[34:35], v[22:23], v[24:25]
	s_waitcnt lgkmcnt(1)
	v_pk_add_f32 v[8:9], v[28:29], v[8:9]
	ds_read_b128 v[22:25], v14 offset:14336
	ds_read_b128 v[26:29], v14 offset:15360
	v_pk_add_f32 v[6:7], v[32:33], v[6:7]
	s_waitcnt lgkmcnt(2)
	v_pk_add_f32 v[4:5], v[30:31], v[4:5]
	v_pk_add_f32 v[2:3], v[34:35], v[2:3]
	s_waitcnt lgkmcnt(1)
	v_pk_add_f32 v[8:9], v[8:9], v[24:25]
	v_pk_add_f32 v[6:7], v[6:7], v[22:23]
	s_waitcnt lgkmcnt(0)
	v_pk_add_f32 v[4:5], v[4:5], v[28:29]
	v_pk_add_f32 v[2:3], v[2:3], v[26:27]
